# speedup vs baseline: 1.0011x; 1.0011x over previous
; #define LAS __attribute__((address_space(3)))
; __device__ void attn_phase(LAS unsigned char* lds, const bf16_t* PROJ, bf16_t* AP, float* LSE) {
;     ...
; #pragma unroll
;         for (int it = 0; it < 8; ++it) { const int idx = tid + 512 * it, row = idx >> 4, ch = idx & 15; *(LAS u32x4*)(Kl + row * KP + ch * 16) = kreg[it]; *(LAS u32x4*)(Vl + row * KP + ch * 16) = vreg[it]; }
;         const int qi = 128 * b + 16 * wave + fr; const size_t qtok = (size_t)(start + r + (qi << dsh));
;         bf16x8 qf[4];
; #pragma unroll
;         for (int ks = 0; ks < 4; ++ks) qf[ks] = *(const bf16x8*)(PROJ + pj(qtok, h * 128 + 32 * ks + 8 * g));
;         __syncthreads();
;         if (item + (int)gridDim.x < 4608) { const AttnItem an = attn_decode(item + gridDim.x); ATTN_ISSUE(an); }
.Lattn_qdone:
	v_add_u32_e32 v0, v131, v138
	s_waitcnt vmcnt(9)
	ds_write_b128 v0, v[8:11]
	v_add_u32_e32 v0, v132, v138
	ds_write_b128 v0, v[4:7]
	v_add_u32_e32 v0, v131, v140
	s_waitcnt vmcnt(7)
	ds_write_b128 v0, v[16:19]
	v_add_u32_e32 v0, v132, v140
	ds_write_b128 v0, v[12:15]
	v_add_u32_e32 v0, v131, v142
	s_waitcnt vmcnt(5)
	ds_write_b128 v0, v[24:27]
	v_add_u32_e32 v0, v132, v142
	ds_write_b128 v0, v[20:23]
	v_add_u32_e32 v0, v131, v144
	s_waitcnt vmcnt(4)
	ds_write_b128 v0, v[32:35]
	v_add_u32_e32 v0, v132, v144
	ds_write_b128 v0, v[28:31]
	v_add_u32_e32 v0, v131, v146
	ds_write_b128 v0, v[36:39]
	v_add_u32_e32 v0, v132, v146
	ds_write_b128 v0, v[40:43]
	v_add_u32_e32 v0, v131, v148
	ds_write_b128 v0, v[44:47]
	v_add_u32_e32 v0, v132, v148
	ds_write_b128 v0, v[48:51]
	v_add_u32_e32 v0, v131, v150
	s_add_i32 s6, s6, s10
	ds_write_b128 v0, v[52:55]
	v_add_u32_e32 v0, v132, v150
	s_cmpk_gt_i32 s6, 0x11ff
	ds_write_b128 v0, v[56:59]
	v_add_u32_e32 v0, v131, v152
	s_cselect_b64 s[0:1], -1, 0
	ds_write_b128 v0, v[60:63]
	v_add_u32_e32 v0, v132, v152
	s_and_b64 vcc, exec, s[0:1]
	ds_write_b128 v0, v[64:67]
	s_waitcnt lgkmcnt(0)
	s_barrier
	s_cmp_eq_u32 s101, 1
	s_cbranch_scc1 .Lattn_noqwait
	s_waitcnt vmcnt(0)
.Lattn_noqwait:
	s_cbranch_vccnz .LBB0_362
	s_ashr_i32 s5, s6, 8
	s_cmp_lt_i32 s5, 6
	s_mov_b32 s2, 0
	s_cbranch_scc1 .LBB0_342
	s_lshr_b32 s2, s6, 8
	s_add_i32 s3, s2, 0xfffa
	s_and_b32 s2, s3, 0xff
	s_mulk_i32 s2, 0xab
	s_bfe_u32 s5, s2, 0x70009
	s_add_i32 s2, s5, 1
	s_mul_i32 s5, s5, 3
	s_sub_i32 s3, s3, s5
	s_and_b32 s2, s2, 0xff
	s_and_b32 s5, s3, 0xff
